# speedup vs baseline: 1.0083x; 1.0030x over previous
;     ...
;   const int rg = (l15 >> 2) & 3;
;   const int gr = (rg == 0) ? 0 : (rg == 1) ? 2 : (rg == 2) ? 3 : 1;
;   const int aoff_r = (wm * (MS * 16) + l15) * 64 + ((quad ^ gr) << 4);
;   const int boff_r = A_BYTES + (wn * 64 + l15) * 64 + ((quad ^ gr) << 4);
; template <int MS>
; DEV void zero_acc(f32x4 (&acc)[MS][4]) {
; #pragma unroll
;   for (int a = 0; a < MS; ++a)
; #pragma unroll
;     for (int b = 0; b < 4; ++b) acc[a][b] = f32x4{0.f, 0.f, 0.f, 0.f};
.LBB0_1415:
	v_lshlrev_b32_e32 v6, 6, v9
	s_mov_b64 s[4:5], 0x4000
	v_and_b32_e32 v241, 0xffffe3c0, v6
	v_bitop3_b32 v242, v10, v9, 48 bitop3:0x78
	v_and_b32_e32 v243, 0x13c0, v6
	v_lshl_add_u64 v[206:207], v[4:5], 0, s[4:5]
	v_lshl_add_u64 v[208:209], v[2:3], 0, s[4:5]
	s_mov_b64 s[4:5], 0
	s_mov_b32 s17, 2
	s_mov_b32 s18, 0
	s_mov_b32 s19, 0
	s_branch .LBB0_1417

;     ...
;   for (int kt = 0; kt < nk; ++kt) {
;     if (NST == 4 && kt + 2 < nk) asm volatile("s_waitcnt vmcnt(%0)" ::"n"(2 * NLD) : "memory");
;     else if (kt + 1 < nk) asm volatile("s_waitcnt vmcnt(%0)" ::"n"(NLD) : "memory");
;     else asm volatile("s_waitcnt vmcnt(0)" ::: "memory");
;     __builtin_amdgcn_s_barrier();
;     const char* st = smem + (kt % NST) * STAGE;
;     bf16x8 af[MS], bfr[4];
; #pragma unroll
;     for (int ms = 0; ms < MS; ++ms) af[ms] = *(const bf16x8*)(st + aoff_r + ms * 1024);
; #pragma unroll
;     for (int ns = 0; ns < 4; ++ns) bfr[ns] = *(const bf16x8*)(st + boff_r + ns * 1024);
;     asm volatile("" ::: "memory");
;     if (kt + NST - 1 < nk) ISSUE(kt + NST - 1)
;     __builtin_amdgcn_s_setprio(1);
; #pragma unroll
;     for (int ms = 0; ms < MS; ++ms)
; #pragma unroll
;       for (int ns = 0; ns < 4; ++ns) acc[ms][ns] = __builtin_amdgcn_mfma_f32_16x16x32_bf16(af[ms], bfr[ns], acc[ms][ns], 0, 0, 0);
;     __builtin_amdgcn_s_setprio(0);
.LBB0_1421:
	s_cmp_eq_u32 s2, 0
	s_cbranch_scc1 .Lk0_wi
	s_mul_hi_u32 s12, s19, 0xaaaaaaab
	s_lshr_b32 s12, s12, 1
	s_mul_i32 s12, s12, 0x12000
	v_subrev_u32_e32 v130, s12, v241
	v_add_u32_e32 v139, s18, v242
	v_add_u32_e32 v130, v139, v130
	v_subrev_u32_e32 v138, s12, v243
	v_add_u32_e32 v150, v139, v138
	s_barrier
	ds_read_b128 v[138:141], v150 offset:16384
	ds_read_b128 v[142:145], v150 offset:17408
	ds_read_b128 v[146:149], v150 offset:18432
	ds_read_b128 v[150:153], v150 offset:19456
	ds_read_b128 v[174:177], v130
	ds_read_b128 v[170:173], v130 offset:1024
	ds_read_b128 v[166:169], v130 offset:2048
	ds_read_b128 v[162:165], v130 offset:3072
	ds_read_b128 v[158:161], v130 offset:4096
	ds_read_b128 v[154:157], v130 offset:5120
	ds_read_b128 v[134:137], v130 offset:6144
	ds_read_b128 v[130:133], v130 offset:7168
	s_cmp_gt_u32 s2, 29
	s_cbranch_scc1 .LBB0_1416
	s_mul_i32 s13, s17, 0xab
	s_bfe_u32 s13, s13, 0x70009
	s_mul_i32 s13, s13, 3
	s_add_i32 s2, s4, 0x4000
	s_sub_i32 s13, s17, s13
	s_and_b32 s2, s2, 0x7c000
	s_and_b32 s13, s13, 0xff
	s_and_b32 s12, s4, 0x2000
	s_mulk_i32 s13, 0x6000
	s_lshl_b32 s2, s2, 1
	s_add_i32 s21, s11, s13
	s_setprio 1
	s_waitcnt lgkmcnt(7)
	v_mfma_f32_16x16x32_bf16 v[38:41], v[174:177], v[138:141], v[38:41]
	v_mfma_f32_16x16x32_bf16 v[122:125], v[174:177], v[142:145], v[122:125]
	v_mfma_f32_16x16x32_bf16 v[126:129], v[174:177], v[146:149], v[126:129]
	v_mfma_f32_16x16x32_bf16 v[118:121], v[174:177], v[150:153], v[118:121]
	v_lshl_add_u64 v[244:245], v[198:199], 0, s[2:3]
	s_waitcnt lgkmcnt(6)
	v_mfma_f32_16x16x32_bf16 v[26:29], v[170:173], v[138:141], v[26:29]
	s_lshl_b32 s12, s12, 1
	v_mfma_f32_16x16x32_bf16 v[110:113], v[170:173], v[142:145], v[110:113]
	s_mov_b32 s13, s3
	v_mfma_f32_16x16x32_bf16 v[114:117], v[170:173], v[146:149], v[114:117]
	v_lshl_add_u64 v[244:245], v[244:245], 0, s[12:13]
	v_mfma_f32_16x16x32_bf16 v[106:109], v[170:173], v[150:153], v[106:109]
	s_mov_b32 m0, s21
	s_waitcnt lgkmcnt(5)
	v_mfma_f32_16x16x32_bf16 v[22:25], v[166:169], v[138:141], v[22:25]
	global_load_lds_dwordx4 v[244:245], off
	v_mfma_f32_16x16x32_bf16 v[98:101], v[166:169], v[142:145], v[98:101]
	v_mfma_f32_16x16x32_bf16 v[102:105], v[166:169], v[146:149], v[102:105]
	v_lshl_add_u64 v[244:245], v[200:201], 0, s[2:3]
	v_mfma_f32_16x16x32_bf16 v[94:97], v[166:169], v[150:153], v[94:97]
	v_lshl_add_u64 v[244:245], v[244:245], 0, s[12:13]
	s_waitcnt lgkmcnt(4)
	v_mfma_f32_16x16x32_bf16 v[18:21], v[162:165], v[138:141], v[18:21]
	s_add_i32 m0, s21, 0x1000
	v_mfma_f32_16x16x32_bf16 v[86:89], v[162:165], v[142:145], v[86:89]
	global_load_lds_dwordx4 v[244:245], off
	v_mfma_f32_16x16x32_bf16 v[90:93], v[162:165], v[146:149], v[90:93]
	v_lshl_add_u64 v[244:245], v[202:203], 0, s[2:3]
	v_mfma_f32_16x16x32_bf16 v[82:85], v[162:165], v[150:153], v[82:85]
	v_lshl_add_u64 v[244:245], v[244:245], 0, s[12:13]
	s_waitcnt lgkmcnt(3)
	v_mfma_f32_16x16x32_bf16 v[14:17], v[158:161], v[138:141], v[14:17]
	v_mfma_f32_16x16x32_bf16 v[74:77], v[158:161], v[142:145], v[74:77]
	s_add_i32 m0, s21, 0x2000
	v_mfma_f32_16x16x32_bf16 v[78:81], v[158:161], v[146:149], v[78:81]
	global_load_lds_dwordx4 v[244:245], off
	v_mfma_f32_16x16x32_bf16 v[70:73], v[158:161], v[150:153], v[70:73]
	v_lshl_add_u64 v[244:245], v[204:205], 0, s[2:3]
	s_waitcnt lgkmcnt(2)
	v_mfma_f32_16x16x32_bf16 v[10:13], v[154:157], v[138:141], v[10:13]
	v_lshl_add_u64 v[244:245], v[244:245], 0, s[12:13]
	v_mfma_f32_16x16x32_bf16 v[62:65], v[154:157], v[142:145], v[62:65]
	s_add_i32 m0, s21, 0x3000
	v_mfma_f32_16x16x32_bf16 v[66:69], v[154:157], v[146:149], v[66:69]
	global_load_lds_dwordx4 v[244:245], off
	v_mfma_f32_16x16x32_bf16 v[58:61], v[154:157], v[150:153], v[58:61]
	s_waitcnt lgkmcnt(1)
	v_mfma_f32_16x16x32_bf16 v[6:9], v[134:137], v[138:141], v[6:9]
	v_lshl_add_u64 v[244:245], v[208:209], 0, s[4:5]
	v_mfma_f32_16x16x32_bf16 v[50:53], v[134:137], v[142:145], v[50:53]
	s_add_i32 m0, s21, 0x4000
	v_mfma_f32_16x16x32_bf16 v[54:57], v[134:137], v[146:149], v[54:57]
	global_load_lds_dwordx4 v[244:245], off
	v_mfma_f32_16x16x32_bf16 v[46:49], v[134:137], v[150:153], v[46:49]
	v_lshl_add_u64 v[244:245], v[206:207], 0, s[4:5]
	s_waitcnt lgkmcnt(0)
	v_mfma_f32_16x16x32_bf16 v[2:5], v[130:133], v[138:141], v[2:5]
	s_add_i32 m0, s21, 0x5000
	v_mfma_f32_16x16x32_bf16 v[34:37], v[130:133], v[142:145], v[34:37]
	global_load_lds_dwordx4 v[244:245], off
	v_mfma_f32_16x16x32_bf16 v[42:45], v[130:133], v[146:149], v[42:45]
	v_mfma_f32_16x16x32_bf16 v[30:33], v[130:133], v[150:153], v[30:33]
	s_setprio 0
	s_branch .Lgt_tail_12
;     ...
;   for (int kt = 0; kt < nk; ++kt) {
;     if (NST == 4 && kt + 2 < nk) asm volatile("s_waitcnt vmcnt(%0)" ::"n"(2 * NLD) : "memory");
;     else if (kt + 1 < nk) asm volatile("s_waitcnt vmcnt(%0)" ::"n"(NLD) : "memory");
;     else asm volatile("s_waitcnt vmcnt(0)" ::: "memory");
;     __builtin_amdgcn_s_barrier();
;     const char* st = smem + (kt % NST) * STAGE;
;     bf16x8 af[MS], bfr[4];
; #pragma unroll
;     for (int ms = 0; ms < MS; ++ms) af[ms] = *(const bf16x8*)(st + aoff_r + ms * 1024);
; #pragma unroll
;     for (int ns = 0; ns < 4; ++ns) bfr[ns] = *(const bf16x8*)(st + boff_r + ns * 1024);
;     asm volatile("" ::: "memory");
;     if (kt + NST - 1 < nk) ISSUE(kt + NST - 1)
;     __builtin_amdgcn_s_setprio(1);
; #pragma unroll
;     for (int ms = 0; ms < MS; ++ms)
; #pragma unroll
;       for (int ns = 0; ns < 4; ++ns) acc[ms][ns] = __builtin_amdgcn_mfma_f32_16x16x32_bf16(af[ms], bfr[ns], acc[ms][ns], 0, 0, 0);
;     __builtin_amdgcn_s_setprio(0);
; template <int MS>
; DEV void zero_acc(f32x4 (&acc)[MS][4]) {
; #pragma unroll
;   for (int a = 0; a < MS; ++a)
; #pragma unroll
;     for (int b = 0; b < 4; ++b) acc[a][b] = f32x4{0.f, 0.f, 0.f, 0.f};
.Lk0_wi:
	s_mul_hi_u32 s12, s19, 0xaaaaaaab
	s_lshr_b32 s12, s12, 1
	s_mul_i32 s12, s12, 0x12000
	v_subrev_u32_e32 v130, s12, v241
	v_add_u32_e32 v139, s18, v242
	v_add_u32_e32 v130, v139, v130
	v_subrev_u32_e32 v138, s12, v243
	v_add_u32_e32 v150, v139, v138
	s_barrier
	ds_read_b128 v[138:141], v150 offset:16384
	ds_read_b128 v[142:145], v150 offset:17408
	ds_read_b128 v[146:149], v150 offset:18432
	ds_read_b128 v[150:153], v150 offset:19456
	ds_read_b128 v[174:177], v130
	ds_read_b128 v[170:173], v130 offset:1024
	ds_read_b128 v[166:169], v130 offset:2048
	ds_read_b128 v[162:165], v130 offset:3072
	ds_read_b128 v[158:161], v130 offset:4096
	ds_read_b128 v[154:157], v130 offset:5120
	ds_read_b128 v[134:137], v130 offset:6144
	ds_read_b128 v[130:133], v130 offset:7168
	s_cmp_gt_u32 s2, 29
	s_cbranch_scc1 .LBB0_1416
	s_mul_i32 s13, s17, 0xab
	s_bfe_u32 s13, s13, 0x70009
	s_mul_i32 s13, s13, 3
	s_add_i32 s2, s4, 0x4000
	s_sub_i32 s13, s17, s13
	s_and_b32 s2, s2, 0x7c000
	s_and_b32 s13, s13, 0xff
	s_and_b32 s12, s4, 0x2000
	s_mulk_i32 s13, 0x6000
	s_lshl_b32 s2, s2, 1
	s_add_i32 s21, s11, s13
	s_setprio 1
	s_waitcnt lgkmcnt(7)
	v_mfma_f32_16x16x32_bf16 v[38:41], v[174:177], v[138:141], 0
	v_mfma_f32_16x16x32_bf16 v[122:125], v[174:177], v[142:145], 0
	v_mfma_f32_16x16x32_bf16 v[126:129], v[174:177], v[146:149], 0
	v_mfma_f32_16x16x32_bf16 v[118:121], v[174:177], v[150:153], 0
	v_lshl_add_u64 v[244:245], v[198:199], 0, s[2:3]
	s_waitcnt lgkmcnt(6)
	v_mfma_f32_16x16x32_bf16 v[26:29], v[170:173], v[138:141], 0
	s_lshl_b32 s12, s12, 1
	v_mfma_f32_16x16x32_bf16 v[110:113], v[170:173], v[142:145], 0
	s_mov_b32 s13, s3
	v_mfma_f32_16x16x32_bf16 v[114:117], v[170:173], v[146:149], 0
	v_lshl_add_u64 v[244:245], v[244:245], 0, s[12:13]
	v_mfma_f32_16x16x32_bf16 v[106:109], v[170:173], v[150:153], 0
	s_mov_b32 m0, s21
	s_waitcnt lgkmcnt(5)
	v_mfma_f32_16x16x32_bf16 v[22:25], v[166:169], v[138:141], 0
	global_load_lds_dwordx4 v[244:245], off
	v_mfma_f32_16x16x32_bf16 v[98:101], v[166:169], v[142:145], 0
	v_mfma_f32_16x16x32_bf16 v[102:105], v[166:169], v[146:149], 0
	v_lshl_add_u64 v[244:245], v[200:201], 0, s[2:3]
	v_mfma_f32_16x16x32_bf16 v[94:97], v[166:169], v[150:153], 0
	v_lshl_add_u64 v[244:245], v[244:245], 0, s[12:13]
	s_waitcnt lgkmcnt(4)
	v_mfma_f32_16x16x32_bf16 v[18:21], v[162:165], v[138:141], 0
	s_add_i32 m0, s21, 0x1000
	v_mfma_f32_16x16x32_bf16 v[86:89], v[162:165], v[142:145], 0
	global_load_lds_dwordx4 v[244:245], off
	v_mfma_f32_16x16x32_bf16 v[90:93], v[162:165], v[146:149], 0
	v_lshl_add_u64 v[244:245], v[202:203], 0, s[2:3]
	v_mfma_f32_16x16x32_bf16 v[82:85], v[162:165], v[150:153], 0
	v_lshl_add_u64 v[244:245], v[244:245], 0, s[12:13]
	s_waitcnt lgkmcnt(3)
	v_mfma_f32_16x16x32_bf16 v[14:17], v[158:161], v[138:141], 0
	v_mfma_f32_16x16x32_bf16 v[74:77], v[158:161], v[142:145], 0
	s_add_i32 m0, s21, 0x2000
	v_mfma_f32_16x16x32_bf16 v[78:81], v[158:161], v[146:149], 0
	global_load_lds_dwordx4 v[244:245], off
	v_mfma_f32_16x16x32_bf16 v[70:73], v[158:161], v[150:153], 0
	v_lshl_add_u64 v[244:245], v[204:205], 0, s[2:3]
	s_waitcnt lgkmcnt(2)
	v_mfma_f32_16x16x32_bf16 v[10:13], v[154:157], v[138:141], 0
	v_lshl_add_u64 v[244:245], v[244:245], 0, s[12:13]
	v_mfma_f32_16x16x32_bf16 v[62:65], v[154:157], v[142:145], 0
	s_add_i32 m0, s21, 0x3000
	v_mfma_f32_16x16x32_bf16 v[66:69], v[154:157], v[146:149], 0
	global_load_lds_dwordx4 v[244:245], off
	v_mfma_f32_16x16x32_bf16 v[58:61], v[154:157], v[150:153], 0
	s_waitcnt lgkmcnt(1)
	v_mfma_f32_16x16x32_bf16 v[6:9], v[134:137], v[138:141], 0
	v_lshl_add_u64 v[244:245], v[208:209], 0, s[4:5]
	v_mfma_f32_16x16x32_bf16 v[50:53], v[134:137], v[142:145], 0
	s_add_i32 m0, s21, 0x4000
	v_mfma_f32_16x16x32_bf16 v[54:57], v[134:137], v[146:149], 0
	global_load_lds_dwordx4 v[244:245], off
	v_mfma_f32_16x16x32_bf16 v[46:49], v[134:137], v[150:153], 0
	v_lshl_add_u64 v[244:245], v[206:207], 0, s[4:5]
	s_waitcnt lgkmcnt(0)
	v_mfma_f32_16x16x32_bf16 v[2:5], v[130:133], v[138:141], 0
	s_add_i32 m0, s21, 0x5000
	v_mfma_f32_16x16x32_bf16 v[34:37], v[130:133], v[142:145], 0
	global_load_lds_dwordx4 v[244:245], off
	v_mfma_f32_16x16x32_bf16 v[42:45], v[130:133], v[146:149], 0
	v_mfma_f32_16x16x32_bf16 v[30:33], v[130:133], v[150:153], 0
	s_setprio 0
	s_branch .Lgt_tail_12
